# attention: base-2 softmax (log2e folded into scale/bias/sink, 33 v_mul per key tile gone); QK groups: next group's 4 K reads + 4 bias reads issued behind the current group's MFMAs, one lgkmcnt wait pe
# speedup vs baseline: 1.0036x; 1.0036x over previous
; #define ATT_ISSUE(kt_) do { const int ktn_ = (kt_); ATT_LD(0, pk0, pv0); ATT_LD(1, pk1, pv1); ATT_LD(2, pk2_, pv2); ATT_LD(3, pk3, pv3); } while (0)
; #define ATT_ST(i, RK, RV) do { const int q = tid + NTHR * (i), row = q >> 4, c16 = q & 15; \
;       *(uint4*)(Ks + row * LDP + c16 * 8) = RK; *(uint4*)(Vs + row * LDV + c16 * 8) = RV; } while (0)
; __device__ __forceinline__ void attn_item(const Params& P, const int pass, const int item, const int wvi) {
;     ...
;   for (int kt = kt_lo; kt <= kt_hi; ++kt) {
;     u16* Ks = (u16*)(smem + (kt & 1) * ATT_SET);
;     u16* Vs = Ks + 128 * LDP;
;     ATT_ST(0, pk0, pv0); ATT_ST(1, pk1, pv1); ATT_ST(2, pk2_, pv2); ATT_ST(3, pk3, pv3);
;     __syncthreads();
;     ATT_ISSUE((kt < kt_hi) ? kt + 1 : kt);
;     f32x4 sc[8];
;     float mx = -INFINITY;
; #pragma unroll
;     for (int t8 = 0; t8 < 8; ++t8) {
;       f32x4 a = f32x4{0.f, 0.f, 0.f, 0.f};
; #pragma unroll
;       for (int kk = 0; kk < 4; ++kk) {
;         bf16x8 kf = *(const bf16x8*)(Ks + (t8 * 16 + fr) * LDP + kk * 32 + fq * 8);
;         a = __builtin_amdgcn_mfma_f32_16x16x32_bf16(kf, qf[kk], a, 0, 0, 0);
;       }
; #pragma unroll
;       for (int j = 0; j < 4; ++j) {
;         const int rel = (kt - 1) * 128 + t8 * 16 + fq * 4 + j - qi;
;         const bool ok = (rel >= -128) && (rel <= 128);
;         const int ri = ok ? rel + 128 : 0;
;         const float v = ok ? (a[j] * scale + fb[ri]) : -INFINITY;
;         a[j] = v;
;         mx = fmaxf(mx, v);
;       }
;       sc[t8] = a;
.LBB0_560:
	s_bitcmp1_b32 s8, 0
	s_cselect_b32 s0, 0x11800, 0
	s_add_i32 s9, s0, 32
	s_cmp_ge_u32 s8, s4
	s_mov_b32 s2, s8
	v_add3_u32 v80, s9, v101, v88
	s_cselect_b64 s[0:1], -1, 0
	s_add_i32 s8, s8, 1
	s_waitcnt vmcnt(7)
	ds_write_b128 v80, v[16:19]
	v_add3_u32 v16, s9, v102, v88
	s_cmp_lt_u32 s2, s4
	s_waitcnt vmcnt(6)
	ds_write_b128 v16, v[20:23] offset:34816
	v_add3_u32 v16, s9, v103, v88
	s_cselect_b32 s2, s8, s2
	s_waitcnt vmcnt(5)
	ds_write_b128 v16, v[24:27]
	v_add3_u32 v16, s9, v104, v88
	s_add_i32 s2, s2, s7
	s_waitcnt vmcnt(4)
	ds_write_b128 v16, v[28:31] offset:34816
	v_add3_u32 v16, s9, v105, v88
	s_ashr_i32 s3, s2, 31
	s_waitcnt vmcnt(3)
	ds_write_b128 v16, v[32:35]
	v_add3_u32 v16, s9, v106, v88
	s_lshl_b64 s[2:3], s[2:3], 7
	s_waitcnt vmcnt(2)
	ds_write_b128 v16, v[36:39] offset:34816
	v_add3_u32 v16, s9, v107, v88
	s_add_u32 s2, s2, s5
	s_waitcnt vmcnt(1)
	ds_write_b128 v16, v[40:43]
	v_add3_u32 v16, s9, v108, v88
	s_addc_u32 s3, s3, s6
	s_waitcnt vmcnt(0)
	ds_write_b128 v16, v[44:47] offset:34816
	v_lshl_add_u64 v[16:17], s[2:3], 0, v[86:87]
	v_lshlrev_b64 v[16:17], 10, v[16:17]
	v_add_u32_e32 v28, s9, v144
	v_lshl_add_u64 v[18:19], v[96:97], 0, v[16:17]
	v_lshl_add_u64 v[20:21], v[98:99], 0, v[16:17]
	v_add_u32_e32 v126, v28, v111
	s_waitcnt lgkmcnt(0)
	s_barrier
	ds_read_b32 v210, v114
	ds_read_b32 v211, v114 offset:4
	ds_read_b32 v212, v114 offset:8
	ds_read_b32 v213, v114 offset:12
	global_load_dwordx4 v[16:19], v[18:19], off
	s_nop 0
	global_load_dwordx4 v[20:23], v[20:21], off
	ds_read_b128 v[32:35], v126
	v_lshl_add_u64 v[24:25], s[2:3], 0, v[90:91]
	v_lshlrev_b64 v[24:25], 10, v[24:25]
	v_lshl_add_u64 v[26:27], v[96:97], 0, v[24:25]
	v_lshl_add_u64 v[28:29], v[98:99], 0, v[24:25]
	global_load_dwordx4 v[24:27], v[26:27], off
	s_nop 0
	global_load_dwordx4 v[28:31], v[28:29], off
	ds_read_b128 v[40:43], v126 offset:64
	ds_read_b128 v[80:83], v126 offset:128
	s_waitcnt lgkmcnt(2)
	v_mfma_f32_16x16x32_bf16 v[44:47], v[32:35], v[0:3], 0
	v_lshl_add_u64 v[36:37], s[2:3], 0, v[92:93]
	v_lshl_add_u64 v[118:119], s[2:3], 0, v[94:95]
	v_lshlrev_b64 v[36:37], 10, v[36:37]
	s_waitcnt lgkmcnt(1)
	v_mfma_f32_16x16x32_bf16 v[40:43], v[40:43], v[4:7], v[44:47]
	v_lshlrev_b64 v[118:119], 10, v[118:119]
	v_lshl_add_u64 v[38:39], v[96:97], 0, v[36:37]
	v_lshl_add_u64 v[36:37], v[98:99], 0, v[36:37]
	v_lshl_add_u64 v[44:45], v[96:97], 0, v[118:119]
	v_lshl_add_u64 v[46:47], v[98:99], 0, v[118:119]
	global_load_dwordx4 v[32:35], v[38:39], off
	s_nop 0
	global_load_dwordx4 v[36:39], v[36:37], off
	ds_read_b128 v[118:121], v126 offset:192
	s_waitcnt lgkmcnt(1)
	v_mfma_f32_16x16x32_bf16 v[80:83], v[80:83], v[8:11], v[40:43]
	s_nop 2
	global_load_dwordx4 v[40:43], v[44:45], off
	s_nop 0
	global_load_dwordx4 v[44:47], v[46:47], off
	v_cmp_gt_u32_e32 vcc, s97, v113
	s_waitcnt lgkmcnt(0)
	v_mfma_f32_16x16x32_bf16 v[80:83], v[118:121], v[12:15], v[80:83]
	ds_read_b128 v[176:179], v126 offset:4352
	ds_read_b128 v[180:183], v126 offset:4416
	ds_read_b128 v[190:193], v126 offset:4480
	ds_read_b128 v[218:221], v126 offset:4544
	ds_read_b32 v214, v114 offset:64
	ds_read_b32 v215, v114 offset:68
	ds_read_b32 v216, v114 offset:72
	ds_read_b32 v217, v114 offset:76
	v_fmamk_f32 v121, v80, 0x3e0293ee, v210
	v_fmamk_f32 v118, v81, 0x3e0293ee, v211
	v_fmamk_f32 v124, v82, 0x3e0293ee, v212
	v_fmamk_f32 v119, v83, 0x3e0293ee, v213
	s_waitcnt lgkmcnt(0)
	v_mfma_f32_16x16x32_bf16 v[80:83], v[176:179], v[0:3], 0
	v_mfma_f32_16x16x32_bf16 v[80:83], v[180:183], v[4:7], v[80:83]
	v_mfma_f32_16x16x32_bf16 v[80:83], v[190:193], v[8:11], v[80:83]
	v_mfma_f32_16x16x32_bf16 v[80:83], v[218:221], v[12:15], v[80:83]
	ds_read_b128 v[222:225], v126 offset:8704
	ds_read_b128 v[226:229], v126 offset:8768
	ds_read_b128 v[230:233], v126 offset:8832
	ds_read_b128 v[234:237], v126 offset:8896
	ds_read_b32 v210, v114 offset:128
	ds_read_b32 v211, v114 offset:132
	ds_read_b32 v212, v114 offset:136
	ds_read_b32 v213, v114 offset:140
	v_fmamk_f32 v122, v80, 0x3e0293ee, v214
	v_fmamk_f32 v120, v81, 0x3e0293ee, v215
	v_fmamk_f32 v125, v82, 0x3e0293ee, v216
	v_fmamk_f32 v123, v83, 0x3e0293ee, v217
	s_waitcnt lgkmcnt(0)
	v_mfma_f32_16x16x32_bf16 v[80:83], v[222:225], v[0:3], 0
	v_mfma_f32_16x16x32_bf16 v[80:83], v[226:229], v[4:7], v[80:83]
	v_mfma_f32_16x16x32_bf16 v[80:83], v[230:233], v[8:11], v[80:83]
	v_mfma_f32_16x16x32_bf16 v[80:83], v[234:237], v[12:15], v[80:83]
	ds_read_b128 v[176:179], v126 offset:13056
	ds_read_b128 v[180:183], v126 offset:13120
	ds_read_b128 v[190:193], v126 offset:13184
	ds_read_b128 v[218:221], v126 offset:13248
	ds_read_b32 v214, v114 offset:192
	ds_read_b32 v215, v114 offset:196
	ds_read_b32 v216, v114 offset:200
	ds_read_b32 v217, v114 offset:204
	v_fmamk_f32 v128, v80, 0x3e0293ee, v210
	v_fmamk_f32 v127, v81, 0x3e0293ee, v211
	v_fmamk_f32 v130, v82, 0x3e0293ee, v212
	v_fmamk_f32 v129, v83, 0x3e0293ee, v213
	s_waitcnt lgkmcnt(0)
	v_mfma_f32_16x16x32_bf16 v[80:83], v[176:179], v[0:3], 0
	v_mfma_f32_16x16x32_bf16 v[80:83], v[180:183], v[4:7], v[80:83]
	v_mfma_f32_16x16x32_bf16 v[80:83], v[190:193], v[8:11], v[80:83]
	v_mfma_f32_16x16x32_bf16 v[80:83], v[218:221], v[12:15], v[80:83]
	ds_read_b128 v[222:225], v126 offset:17408
	ds_read_b128 v[226:229], v126 offset:17472
	ds_read_b128 v[230:233], v126 offset:17536
	ds_read_b128 v[234:237], v126 offset:17600
	ds_read_b32 v210, v114 offset:256
	ds_read_b32 v211, v114 offset:260
	ds_read_b32 v212, v114 offset:264
	ds_read_b32 v213, v114 offset:268
	v_fmamk_f32 v136, v80, 0x3e0293ee, v214
	v_fmamk_f32 v131, v81, 0x3e0293ee, v215
	v_fmamk_f32 v138, v82, 0x3e0293ee, v216
	v_fmamk_f32 v139, v83, 0x3e0293ee, v217
	s_waitcnt lgkmcnt(0)
; __device__ __forceinline__ void attn_item(const Params& P, const int pass, const int item, const int wvi) {
;     ...
;     for (int t8 = 0; t8 < 8; ++t8) {
;       f32x4 a = f32x4{0.f, 0.f, 0.f, 0.f};
; #pragma unroll
;       for (int kk = 0; kk < 4; ++kk) {
;         bf16x8 kf = *(const bf16x8*)(Ks + (t8 * 16 + fr) * LDP + kk * 32 + fq * 8);
;         a = __builtin_amdgcn_mfma_f32_16x16x32_bf16(kf, qf[kk], a, 0, 0, 0);
;       }
; #pragma unroll
;       for (int j = 0; j < 4; ++j) {
;         const int rel = (kt - 1) * 128 + t8 * 16 + fq * 4 + j - qi;
;         const bool ok = (rel >= -128) && (rel <= 128);
;         const int ri = ok ? rel + 128 : 0;
;         const float v = ok ? (a[j] * scale + fb[ri]) : -INFINITY;
;         a[j] = v;
;         mx = fmaxf(mx, v);
;       }
;       sc[t8] = a;
;     }
;     mx = fmaxf(mx, shfl_src(mx, lane ^ 16));
;     mx = fmaxf(mx, shfl_src(mx, lane ^ 32));
;     const float mnew = fmaxf(mrun, mx);
;     const float alpha = __expf(mrun - mnew);
;     float psum = 0.f;
; #pragma unroll
;     for (int t8 = 0; t8 < 8; ++t8)
; #pragma unroll
;       for (int j = 0; j < 4; ++j) { const float pv = __expf(sc[t8][j] - mnew); sc[t8][j] = pv; psum += pv; }
;     psum += shfl_src(psum, lane ^ 16);
;     psum += shfl_src(psum, lane ^ 32);
;     lrun = lrun * alpha + psum;
;     mrun = mnew;
; #pragma unroll
;     for (int d8 = 0; d8 < 8; ++d8)
; #pragma unroll
;       for (int j = 0; j < 4; ++j) oacc[d8][j] *= alpha;
	v_mfma_f32_16x16x32_bf16 v[80:83], v[222:225], v[0:3], 0
	v_mfma_f32_16x16x32_bf16 v[80:83], v[226:229], v[4:7], v[80:83]
	v_mfma_f32_16x16x32_bf16 v[80:83], v[230:233], v[8:11], v[80:83]
	v_mfma_f32_16x16x32_bf16 v[80:83], v[234:237], v[12:15], v[80:83]
	ds_read_b128 v[176:179], v126 offset:21760
	ds_read_b128 v[180:183], v126 offset:21824
	ds_read_b128 v[190:193], v126 offset:21888
	ds_read_b128 v[218:221], v126 offset:21952
	ds_read_b32 v214, v114 offset:320
	ds_read_b32 v215, v114 offset:324
	ds_read_b32 v216, v114 offset:328
	ds_read_b32 v217, v114 offset:332
	v_fmamk_f32 v141, v80, 0x3e0293ee, v210
	v_fmamk_f32 v140, v81, 0x3e0293ee, v211
	v_fmamk_f32 v143, v82, 0x3e0293ee, v212
	v_fmamk_f32 v142, v83, 0x3e0293ee, v213
	s_waitcnt lgkmcnt(0)
	v_mfma_f32_16x16x32_bf16 v[80:83], v[176:179], v[0:3], 0
	v_mfma_f32_16x16x32_bf16 v[80:83], v[180:183], v[4:7], v[80:83]
	v_mfma_f32_16x16x32_bf16 v[80:83], v[190:193], v[8:11], v[80:83]
	v_mfma_f32_16x16x32_bf16 v[80:83], v[218:221], v[12:15], v[80:83]
	ds_read_b128 v[222:225], v126 offset:26112
	ds_read_b128 v[226:229], v126 offset:26176
	ds_read_b128 v[230:233], v126 offset:26240
	ds_read_b128 v[234:237], v126 offset:26304
	ds_read_b32 v210, v114 offset:384
	ds_read_b32 v211, v114 offset:388
	ds_read_b32 v212, v114 offset:392
	ds_read_b32 v213, v114 offset:396
	v_fmamk_f32 v149, v80, 0x3e0293ee, v214
	v_fmamk_f32 v148, v81, 0x3e0293ee, v215
	v_fmamk_f32 v152, v82, 0x3e0293ee, v216
	v_fmamk_f32 v151, v83, 0x3e0293ee, v217
	s_waitcnt lgkmcnt(0)
	v_mfma_f32_16x16x32_bf16 v[80:83], v[222:225], v[0:3], 0
	v_mfma_f32_16x16x32_bf16 v[80:83], v[226:229], v[4:7], v[80:83]
	v_mfma_f32_16x16x32_bf16 v[80:83], v[230:233], v[8:11], v[80:83]
	v_mfma_f32_16x16x32_bf16 v[80:83], v[234:237], v[12:15], v[80:83]
	ds_read_b128 v[176:179], v126 offset:30464
	ds_read_b128 v[180:183], v126 offset:30528
	ds_read_b128 v[190:193], v126 offset:30592
	ds_read_b128 v[218:221], v126 offset:30656
	ds_read_b32 v214, v114 offset:448
	ds_read_b32 v215, v114 offset:452
	ds_read_b32 v216, v114 offset:456
	ds_read_b32 v217, v114 offset:460
	v_fmamk_f32 v154, v80, 0x3e0293ee, v210
	v_fmamk_f32 v153, v81, 0x3e0293ee, v211
	v_fmamk_f32 v156, v82, 0x3e0293ee, v212
	v_fmamk_f32 v155, v83, 0x3e0293ee, v213
	s_waitcnt lgkmcnt(0)
	v_mfma_f32_16x16x32_bf16 v[80:83], v[176:179], v[0:3], 0
	v_mfma_f32_16x16x32_bf16 v[80:83], v[180:183], v[4:7], v[80:83]
	v_mfma_f32_16x16x32_bf16 v[80:83], v[190:193], v[8:11], v[80:83]
	v_mfma_f32_16x16x32_bf16 v[80:83], v[218:221], v[12:15], v[80:83]
	s_nop 7
	v_fmamk_f32 v158, v80, 0x3e0293ee, v214
	v_fmamk_f32 v157, v81, 0x3e0293ee, v215
	v_fmamk_f32 v159, v82, 0x3e0293ee, v216
	v_fmamk_f32 v80, v83, 0x3e0293ee, v217
	s_mov_b32 s2, 0xff800000
	v_max3_f32 v81, v121, s2, v118
	v_max3_f32 v81, v81, v124, v119
	v_max3_f32 v81, v81, v122, v120
	v_max3_f32 v81, v81, v125, v123
	v_max3_f32 v81, v81, v128, v127
	v_max3_f32 v81, v81, v130, v129
	v_max3_f32 v81, v81, v136, v131
	v_max3_f32 v81, v81, v138, v139
	v_max3_f32 v81, v81, v141, v140
	v_max3_f32 v81, v81, v143, v142
	v_max3_f32 v81, v81, v149, v148
	v_max3_f32 v81, v81, v152, v151
	v_max3_f32 v81, v81, v154, v153
	v_max3_f32 v81, v81, v156, v155
	v_max3_f32 v81, v81, v158, v157
	v_max3_f32 v81, v81, v159, v80
	ds_bpermute_b32 v82, v109, v81
	v_add_u32_e32 v113, 0x80, v113
	v_add_u32_e32 v114, 0x200, v114
	s_andn2_b64 vcc, exec, s[0:1]
	s_waitcnt lgkmcnt(0)
	v_max_f32_e32 v82, v82, v82
	v_max_f32_e32 v81, v81, v82
	ds_bpermute_b32 v82, v110, v81
	s_waitcnt lgkmcnt(0)
	v_max3_f32 v81, v117, v81, v82
	v_sub_f32_e32 v82, v117, v81
	v_sub_f32_e32 v117, v118, v81
	v_exp_f32_e32 v147, v117
	v_sub_f32_e32 v117, v124, v81
	v_exp_f32_e32 v150, v117
	v_sub_f32_e32 v117, v119, v81
	v_exp_f32_e32 v164, v117
	v_sub_f32_e32 v117, v122, v81
	v_exp_f32_e32 v166, v117
	v_sub_f32_e32 v117, v120, v81
	v_exp_f32_e32 v172, v117
	v_sub_f32_e32 v117, v125, v81
	v_exp_f32_e32 v173, v117
	v_sub_f32_e32 v117, v123, v81
	v_exp_f32_e32 v174, v117
	v_sub_f32_e32 v117, v128, v81
	v_exp_f32_e32 v132, v117
	v_sub_f32_e32 v117, v127, v81
	v_exp_f32_e32 v133, v117
	v_sub_f32_e32 v117, v130, v81
	v_exp_f32_e32 v134, v117
	v_sub_f32_e32 v117, v129, v81
	v_sub_f32_e32 v83, v121, v81
	v_exp_f32_e32 v135, v117
	v_sub_f32_e32 v117, v136, v81
	v_exp_f32_e32 v146, v83
	v_exp_f32_e32 v136, v117
	v_sub_f32_e32 v117, v131, v81
	v_exp_f32_e32 v137, v117
	v_sub_f32_e32 v117, v138, v81
	v_add_f32_e32 v83, 0, v146
	v_add_f32_e32 v83, v147, v83
	v_exp_f32_e32 v138, v117
	v_sub_f32_e32 v117, v139, v81
	v_add_f32_e32 v83, v150, v83
	v_add_f32_e32 v83, v164, v83
	v_exp_f32_e32 v139, v117
	v_sub_f32_e32 v117, v141, v81
	v_add_f32_e32 v83, v166, v83
	v_add_f32_e32 v83, v172, v83
	v_exp_f32_e32 v124, v117
	v_sub_f32_e32 v117, v140, v81
	v_add_f32_e32 v83, v173, v83
	v_add_f32_e32 v83, v174, v83
	v_exp_f32_e32 v125, v117
	v_sub_f32_e32 v117, v143, v81
	v_add_f32_e32 v83, v132, v83
	v_add_f32_e32 v83, v133, v83
	v_exp_f32_e32 v126, v117
	v_sub_f32_e32 v117, v142, v81
	v_add_f32_e32 v83, v134, v83
	v_add_f32_e32 v83, v135, v83
	v_exp_f32_e32 v127, v117
	v_sub_f32_e32 v117, v149, v81
	v_add_f32_e32 v83, v136, v83
	v_add_f32_e32 v83, v137, v83
	v_exp_f32_e32 v128, v117
	v_sub_f32_e32 v117, v148, v81
	v_add_f32_e32 v83, v138, v83
	v_add_f32_e32 v83, v139, v83
	v_exp_f32_e32 v129, v117
	v_sub_f32_e32 v117, v152, v81
	v_add_f32_e32 v83, v124, v83
	v_add_f32_e32 v83, v125, v83
	v_exp_f32_e32 v130, v117
	v_sub_f32_e32 v117, v151, v81
	v_add_f32_e32 v83, v126, v83
	v_add_f32_e32 v83, v127, v83
	v_exp_f32_e32 v131, v117
	v_add_f32_e32 v83, v128, v83
	v_add_f32_e32 v83, v129, v83
	v_add_f32_e32 v83, v130, v83
	v_add_f32_e32 v117, v131, v83
	v_sub_f32_e32 v83, v154, v81
	v_exp_f32_e32 v83, v83
	v_sub_f32_e32 v80, v80, v81
	v_add_f32_e32 v118, v83, v117
	v_sub_f32_e32 v117, v153, v81
	v_exp_f32_e32 v117, v117
	s_nop 0
	v_add_f32_e32 v119, v117, v118
	v_sub_f32_e32 v118, v156, v81
	v_exp_f32_e32 v118, v118
	s_nop 0
	v_add_f32_e32 v120, v118, v119
	v_sub_f32_e32 v119, v155, v81
	v_exp_f32_e32 v119, v119
	s_nop 0
	v_add_f32_e32 v121, v119, v120
	v_sub_f32_e32 v120, v158, v81
	v_exp_f32_e32 v120, v120
	s_nop 0
	v_add_f32_e32 v122, v120, v121
	v_sub_f32_e32 v121, v157, v81
	v_exp_f32_e32 v121, v121
	s_nop 0
	v_add_f32_e32 v123, v121, v122
	v_sub_f32_e32 v122, v159, v81
	v_exp_f32_e32 v122, v122
	s_nop 0
	v_add_f32_e32 v140, v122, v123
	v_exp_f32_e32 v123, v80
	v_exp_f32_e32 v80, v82
	v_add_f32_e32 v140, v123, v140
	ds_bpermute_b32 v82, v109, v140
	v_pk_mul_f32 v[160:161], v[60:61], v[80:81] op_sel_hi:[1,0]
	v_pk_mul_f32 v[162:163], v[62:63], v[80:81] op_sel_hi:[1,0]
	v_pk_mul_f32 v[168:169], v[64:65], v[80:81] op_sel_hi:[1,0]
	v_pk_mul_f32 v[170:171], v[66:67], v[80:81] op_sel_hi:[1,0]
	s_waitcnt lgkmcnt(0)
; __device__ __forceinline__ void attn_item(const Params& P, const int pass, const int item, const int wvi) {
;     ...
;     psum += shfl_src(psum, lane ^ 16);
;     psum += shfl_src(psum, lane ^ 32);
;     lrun = lrun * alpha + psum;
;     mrun = mnew;
; #pragma unroll
;     for (int d8 = 0; d8 < 8; ++d8)
; #pragma unroll
;       for (int j = 0; j < 4; ++j) oacc[d8][j] *= alpha;
; #pragma unroll
;     for (int kp = 0; kp < 4; ++kp) {
;       const bf16x8 pf = pack8(sc[2 * kp][0], sc[2 * kp][1], sc[2 * kp][2], sc[2 * kp][3],
;                               sc[2 * kp + 1][0], sc[2 * kp + 1][1], sc[2 * kp + 1][2], sc[2 * kp + 1][3]);
; #pragma unroll
;       for (int d8 = 0; d8 < 8; ++d8) {
;         const u16* va = Vs + (kp * 32 + fq * 4 + (fr >> 2)) * LDV + d8 * 16 + (fr & 3) * 4;
;         s16x4 v0 = ldtr(va), v1 = ldtr(va + 16 * LDV);
;         oacc[d8] = __builtin_amdgcn_mfma_f32_16x16x32_bf16(cat8(v0, v1), pf, oacc[d8], 0, 0, 0);
;       }
;     }
	v_add_f32_e32 v82, v140, v82
	v_pk_mul_f32 v[140:141], v[48:49], v[80:81] op_sel_hi:[1,0]
	v_pk_mul_f32 v[48:49], v[76:77], v[80:81] op_sel_hi:[1,0]
	v_add3_u32 v77, s9, v115, v112
	ds_read_b64_tr_b16 v[62:63], v77 offset:39424
	ds_read_b64_tr_b16 v[60:61], v77 offset:34816
	ds_read_b64_tr_b16 v[64:65], v77 offset:34848
	ds_read_b64_tr_b16 v[66:67], v77 offset:39456
	ds_bpermute_b32 v148, v110, v82
	v_pk_mul_f32 v[142:143], v[50:51], v[80:81] op_sel_hi:[1,0]
	v_pk_mul_f32 v[152:153], v[56:57], v[80:81] op_sel_hi:[1,0]
	v_pk_mul_f32 v[154:155], v[58:59], v[80:81] op_sel_hi:[1,0]
	v_pk_mul_f32 v[156:157], v[52:53], v[80:81] op_sel_hi:[1,0]
	v_pk_mul_f32 v[158:159], v[54:55], v[80:81] op_sel_hi:[1,0]
	v_cvt_pk_bf16_f32 v52, v146, v147
	v_cvt_pk_bf16_f32 v53, v150, v164
	v_cvt_pk_bf16_f32 v54, v166, v172
	v_cvt_pk_bf16_f32 v55, v173, v174
	v_pk_mul_f32 v[56:57], v[72:73], v[80:81] op_sel_hi:[1,0]
	v_pk_mul_f32 v[58:59], v[74:75], v[80:81] op_sel_hi:[1,0]
	s_waitcnt lgkmcnt(0)
	v_add_f32_e32 v82, v82, v148
	v_mfma_f32_16x16x32_bf16 v[60:63], v[60:63], v[52:55], v[140:143]
	ds_read_b64_tr_b16 v[72:73], v77 offset:34880
	ds_read_b64_tr_b16 v[74:75], v77 offset:39488
	s_nop 0
	ds_read_b64_tr_b16 v[140:141], v77 offset:34912
	ds_read_b64_tr_b16 v[142:143], v77 offset:39520
	ds_read_b64_tr_b16 v[146:147], v77 offset:34944
	ds_read_b64_tr_b16 v[148:149], v77 offset:39552
	v_mfma_f32_16x16x32_bf16 v[64:67], v[64:67], v[52:55], v[152:155]
	ds_read_b64_tr_b16 v[150:151], v77 offset:34976
	s_nop 1
	ds_read_b64_tr_b16 v[152:153], v77 offset:39584
	v_pk_mul_f32 v[68:69], v[68:69], v[80:81] op_sel_hi:[1,0]
	v_pk_mul_f32 v[70:71], v[70:71], v[80:81] op_sel_hi:[1,0]
	v_pk_mul_f32 v[50:51], v[78:79], v[80:81] op_sel_hi:[1,0]
	s_waitcnt lgkmcnt(6)
	v_mfma_f32_16x16x32_bf16 v[72:75], v[72:75], v[52:55], v[156:159]
	v_add_u32_e32 v76, 0x8800, v77
	v_fmac_f32_e32 v82, v116, v80
	s_waitcnt lgkmcnt(0)
	v_mfma_f32_16x16x32_bf16 v[68:71], v[150:153], v[52:55], v[68:71]
	ds_read_b64_tr_b16 v[150:151], v77 offset:35008
	ds_read_b64_tr_b16 v[152:153], v77 offset:39616
	s_waitcnt lgkmcnt(0)
	v_mfma_f32_16x16x32_bf16 v[56:59], v[150:153], v[52:55], v[56:59]
	ds_read_b64_tr_b16 v[150:151], v77 offset:35040
	ds_read_b64_tr_b16 v[152:153], v77 offset:39648
	v_mfma_f32_16x16x32_bf16 v[140:143], v[140:143], v[52:55], v[160:163]
	v_mfma_f32_16x16x32_bf16 v[146:149], v[146:149], v[52:55], v[168:171]
	s_waitcnt lgkmcnt(0)
	v_mfma_f32_16x16x32_bf16 v[48:51], v[150:153], v[52:55], v[48:51]
	v_cvt_pk_bf16_f32 v52, v132, v133
	v_cvt_pk_bf16_f32 v53, v134, v135
	ds_read_b64_tr_b16 v[132:133], v77 offset:44032
	ds_read_b64_tr_b16 v[134:135], v77 offset:48640
	v_cvt_pk_bf16_f32 v54, v136, v137
	v_cvt_pk_bf16_f32 v55, v138, v139
	s_waitcnt lgkmcnt(0)
	s_nop 0
	v_mfma_f32_16x16x32_bf16 v[60:63], v[132:135], v[52:55], v[60:63]
	ds_read_b64_tr_b16 v[132:133], v77 offset:44064
	ds_read_b64_tr_b16 v[134:135], v77 offset:48672
	s_waitcnt lgkmcnt(0)
	v_mfma_f32_16x16x32_bf16 v[64:67], v[132:135], v[52:55], v[64:67]
	ds_read_b64_tr_b16 v[132:133], v77 offset:44096
	ds_read_b64_tr_b16 v[134:135], v77 offset:48704
	s_waitcnt lgkmcnt(0)
	v_mfma_f32_16x16x32_bf16 v[72:75], v[132:135], v[52:55], v[72:75]
	ds_read_b64_tr_b16 v[132:133], v77 offset:44128
	ds_read_b64_tr_b16 v[134:135], v77 offset:48736
	ds_read_b64_tr_b16 v[136:137], v77 offset:44160
	ds_read_b64_tr_b16 v[138:139], v77 offset:48768
	s_waitcnt lgkmcnt(2)
	v_mfma_f32_16x16x32_bf16 v[132:135], v[132:135], v[52:55], v[140:143]
	s_nop 2
	ds_read_b64_tr_b16 v[140:141], v77 offset:44192
	ds_read_b64_tr_b16 v[142:143], v77 offset:48800
	s_waitcnt lgkmcnt(0)
	v_mfma_f32_16x16x32_bf16 v[68:71], v[140:143], v[52:55], v[68:71]
	ds_read_b64_tr_b16 v[140:141], v77 offset:44224
	ds_read_b64_tr_b16 v[142:143], v77 offset:48832
	s_waitcnt lgkmcnt(0)
; __device__ __forceinline__ void attn_item(const Params& P, const int pass, const int item, const int wvi) {
;     ...
;     for (int kp = 0; kp < 4; ++kp) {
;       const bf16x8 pf = pack8(sc[2 * kp][0], sc[2 * kp][1], sc[2 * kp][2], sc[2 * kp][3],
;                               sc[2 * kp + 1][0], sc[2 * kp + 1][1], sc[2 * kp + 1][2], sc[2 * kp + 1][3]);
; #pragma unroll
;       for (int d8 = 0; d8 < 8; ++d8) {
;         const u16* va = Vs + (kp * 32 + fq * 4 + (fr >> 2)) * LDV + d8 * 16 + (fr & 3) * 4;
;         s16x4 v0 = ldtr(va), v1 = ldtr(va + 16 * LDV);
;         oacc[d8] = __builtin_amdgcn_mfma_f32_16x16x32_bf16(cat8(v0, v1), pf, oacc[d8], 0, 0, 0);
;       }
;     }
	v_mfma_f32_16x16x32_bf16 v[56:59], v[140:143], v[52:55], v[56:59]
	ds_read_b64_tr_b16 v[140:141], v77 offset:44256
	ds_read_b64_tr_b16 v[142:143], v77 offset:48864
	v_mfma_f32_16x16x32_bf16 v[136:139], v[136:139], v[52:55], v[146:149]
	s_waitcnt lgkmcnt(0)
	v_mfma_f32_16x16x32_bf16 v[48:51], v[140:143], v[52:55], v[48:51]
	v_cvt_pk_bf16_f32 v52, v124, v125
	v_cvt_pk_bf16_f32 v53, v126, v127
	ds_read_b64_tr_b16 v[124:125], v77 offset:53248
	ds_read_b64_tr_b16 v[126:127], v77 offset:57856
	v_cvt_pk_bf16_f32 v54, v128, v129
	v_cvt_pk_bf16_f32 v55, v130, v131
	v_cvt_pk_bf16_f32 v140, v83, v117
	v_cvt_pk_bf16_f32 v141, v118, v119
	s_waitcnt lgkmcnt(0)
	v_mfma_f32_16x16x32_bf16 v[60:63], v[124:127], v[52:55], v[60:63]
	ds_read_b64_tr_b16 v[124:125], v77 offset:53280
	ds_read_b64_tr_b16 v[126:127], v77 offset:57888
	v_cvt_pk_bf16_f32 v142, v120, v121
	v_cvt_pk_bf16_f32 v143, v122, v123
	s_waitcnt lgkmcnt(0)
	v_mfma_f32_16x16x32_bf16 v[64:67], v[124:127], v[52:55], v[64:67]
	ds_read_b64_tr_b16 v[124:125], v77 offset:53312
	ds_read_b64_tr_b16 v[126:127], v77 offset:57920
	s_waitcnt lgkmcnt(0)
	v_mfma_f32_16x16x32_bf16 v[72:75], v[124:127], v[52:55], v[72:75]
	ds_read_b64_tr_b16 v[124:125], v77 offset:53344
	ds_read_b64_tr_b16 v[126:127], v77 offset:57952
	ds_read_b64_tr_b16 v[128:129], v77 offset:53376
	ds_read_b64_tr_b16 v[130:131], v77 offset:57984
	s_waitcnt lgkmcnt(2)
	v_mfma_f32_16x16x32_bf16 v[124:127], v[124:127], v[52:55], v[132:135]
	s_nop 2
	ds_read_b64_tr_b16 v[132:133], v77 offset:53408
	ds_read_b64_tr_b16 v[134:135], v77 offset:58016
	s_waitcnt lgkmcnt(0)
	v_mfma_f32_16x16x32_bf16 v[68:71], v[132:135], v[52:55], v[68:71]
	ds_read_b64_tr_b16 v[132:133], v77 offset:53440
	ds_read_b64_tr_b16 v[134:135], v77 offset:58048
	s_waitcnt lgkmcnt(0)
	v_mfma_f32_16x16x32_bf16 v[132:135], v[132:135], v[52:55], v[56:59]
	s_nop 2
	ds_read_b64_tr_b16 v[56:57], v77 offset:53472
	ds_read_b64_tr_b16 v[58:59], v77 offset:58080
	v_mfma_f32_16x16x32_bf16 v[128:131], v[128:131], v[52:55], v[136:139]
	s_waitcnt lgkmcnt(0)
	v_mfma_f32_16x16x32_bf16 v[136:139], v[56:59], v[52:55], v[48:51]
	s_nop 2
	ds_read_b64_tr_b16 v[48:49], v77 offset:62464
	ds_read_b64_tr_b16 v[50:51], v76 offset:32256
	ds_read_b64_tr_b16 v[54:55], v76 offset:32288
	ds_read_b64_tr_b16 v[52:53], v77 offset:62496
	s_waitcnt lgkmcnt(0)
	v_mfma_f32_16x16x32_bf16 v[56:59], v[52:55], v[140:143], v[64:67]
	ds_read_b64_tr_b16 v[52:53], v77 offset:62528
	ds_read_b64_tr_b16 v[54:55], v76 offset:32320
	v_mfma_f32_16x16x32_bf16 v[48:51], v[48:51], v[140:143], v[60:63]
	s_nop 2
	ds_read_b64_tr_b16 v[60:61], v77 offset:62560
	ds_read_b64_tr_b16 v[62:63], v76 offset:32352
	ds_read_b64_tr_b16 v[64:65], v77 offset:62592
	ds_read_b64_tr_b16 v[66:67], v76 offset:32384
	s_waitcnt lgkmcnt(4)
	v_mfma_f32_16x16x32_bf16 v[52:55], v[52:55], v[140:143], v[72:75]
	s_nop 2
	ds_read_b64_tr_b16 v[72:73], v77 offset:62624
	ds_read_b64_tr_b16 v[74:75], v76 offset:32416
	s_waitcnt lgkmcnt(0)
	v_mfma_f32_16x16x32_bf16 v[68:71], v[72:75], v[140:143], v[68:71]
	ds_read_b64_tr_b16 v[72:73], v77 offset:62656
	ds_read_b64_tr_b16 v[74:75], v76 offset:32448
	ds_read_b64_tr_b16 v[118:119], v77 offset:62688
	ds_read_b64_tr_b16 v[120:121], v76 offset:32480
	v_mfma_f32_16x16x32_bf16 v[60:63], v[60:63], v[140:143], v[124:127]
	v_mfma_f32_16x16x32_bf16 v[64:67], v[64:67], v[140:143], v[128:131]
	s_waitcnt lgkmcnt(2)
	v_mfma_f32_16x16x32_bf16 v[72:75], v[72:75], v[140:143], v[132:135]
	s_waitcnt lgkmcnt(0)
	v_mfma_f32_16x16x32_bf16 v[76:79], v[118:121], v[140:143], v[136:139]
	s_cbranch_vccz .LBB0_626
	v_mov_b32_e32 v117, v81
	v_mov_b32_e32 v116, v82
	s_branch .LBB0_560
